# attention epilogue denominator reduction via v_permlane16/32_swap instead of two ds_bpermute round trips
# baseline (speedup 1.0000x reference)
; __device__ __forceinline__ bf16_t f2bf(float f) { unsigned u = __float_as_uint(f); u += 0x7FFFu + ((u >> 16) & 1u); return (bf16_t)(u >> 16); }
; __device__ __forceinline__ float bf2f(bf16_t b) { return __uint_as_float(((unsigned)b) << 16); }
; __device__ void attn_phase(PP p, int layer) {
;     ...
;         float ltot = lrun + __shfl_xor(lrun, 16); ltot += __shfl_xor(ltot, 32);
;         const float inv = 1.0f / ltot;
; #pragma unroll
;         for (int jj = 0; jj < 4; ++jj) { const float ij = __shfl(inv, quad * 4 + jj); const int tok = tq0 + quad * 4 + jj;
; #pragma unroll
;             for (int dt = 0; dt < 4; ++dt) { const int d = dt * 16 + qi; const float z = bf2f(PROJ[(size_t)tok * NIN + 1536 + head * 64 + d]);
;                 U[(size_t)tok * DM + head * 64 + d] = f2bf(O[dt][jj] * ij * z); } }
.LBB0_360:
	s_or_b64 exec, exec, s[62:63]
	v_mov_b32_e32 v16, v24
	v_mov_b32_e32 v17, v24
	v_lshlrev_b32_e32 v162, 1, v98
	s_nop 1
	v_permlane16_swap_b32 v17, v16
	v_add_f32_e32 v16, v16, v17
	v_mov_b32_e32 v17, v16
	s_nop 1
	v_permlane32_swap_b32 v17, v16
	v_add_f32_e32 v16, v16, v17
	v_div_scale_f32 v17, s[6:7], v16, v16, 1.0
	v_rcp_f32_e32 v18, v17
	s_nop 0
	v_fma_f32 v19, -v17, v18, 1.0
	v_fmac_f32_e32 v18, v19, v18
	v_div_scale_f32 v19, vcc, 1.0, v16, 1.0
	v_mul_f32_e32 v20, v19, v18
	v_fma_f32 v21, -v17, v20, v19
	v_fmac_f32_e32 v20, v21, v18
	v_fma_f32 v17, -v17, v20, v19
	v_div_fmas_f32 v17, v17, v18, v20
	v_add_u32_e32 v20, v97, v139
	v_lshl_add_u64 v[18:19], s[64:65], 0, v[162:163]
	v_mad_i64_i32 v[22:23], s[6:7], v20, s68, v[18:19]
	v_mov_b32_e32 v97, v163
	v_ashrrev_i32_e32 v21, 31, v20
	v_lshl_add_u64 v[22:23], v[22:23], 0, v[96:97]
	v_lshlrev_b64 v[24:25], 12, v[20:21]
	global_load_ushort v210, v[22:23], off offset:3072
	global_load_ushort v211, v[22:23], off offset:3104
	global_load_ushort v212, v[22:23], off offset:3136
	global_load_ushort v213, v[22:23], off offset:3168
	s_mov_b64 s[6:7], 0x7000
	s_nop 0
	v_lshl_add_u64 v[226:227], v[22:23], 0, s[6:7]
	global_load_ushort v214, v[226:227], off offset:3072
	global_load_ushort v215, v[226:227], off offset:3104
	global_load_ushort v216, v[226:227], off offset:3136
	global_load_ushort v217, v[226:227], off offset:3168
	s_mov_b64 s[6:7], 0xe000
	s_nop 0
	v_lshl_add_u64 v[226:227], v[22:23], 0, s[6:7]
	global_load_ushort v218, v[226:227], off offset:3072
	global_load_ushort v219, v[226:227], off offset:3104
	global_load_ushort v220, v[226:227], off offset:3136
	global_load_ushort v221, v[226:227], off offset:3168
	s_mov_b64 s[6:7], 0x15000
	s_nop 0
	v_lshl_add_u64 v[226:227], v[22:23], 0, s[6:7]
	global_load_ushort v222, v[226:227], off offset:3072
	global_load_ushort v223, v[226:227], off offset:3104
	global_load_ushort v224, v[226:227], off offset:3136
	global_load_ushort v225, v[226:227], off offset:3168
	v_div_fixup_f32 v26, v17, v16, 1.0
	ds_bpermute_b32 v27, v140, v26
	v_lshl_add_u64 v[16:17], s[48:49], 0, v[162:163]
	v_lshl_add_u64 v[24:25], v[16:17], 0, v[24:25]
	v_lshl_add_u64 v[24:25], v[24:25], 0, v[96:97]
	s_waitcnt lgkmcnt(0)
	v_mul_f32_e32 v12, v12, v27
	v_mul_f32_e32 v8, v8, v27
	v_mul_f32_e32 v4, v4, v27
	v_mul_f32_e32 v0, v0, v27
	s_waitcnt vmcnt(0)
	v_mov_b32_e32 v21, v210
	v_lshlrev_b32_e32 v21, 16, v21
	v_mul_f32_e32 v12, v12, v21
	v_bfe_u32 v21, v12, 16, 1
	v_add3_u32 v12, v12, v21, s69
	global_store_short_d16_hi v[24:25], v12, off
	v_mov_b32_e32 v12, v211
	s_nop 0
	v_lshlrev_b32_e32 v12, 16, v12
	v_mul_f32_e32 v8, v8, v12
	v_bfe_u32 v12, v8, 16, 1
	v_add3_u32 v8, v8, v12, s69
	global_store_short_d16_hi v[24:25], v8, off offset:32
	v_mov_b32_e32 v8, v212
	s_nop 0
	v_lshlrev_b32_e32 v8, 16, v8
	v_mul_f32_e32 v4, v4, v8
	v_bfe_u32 v8, v4, 16, 1
	v_add3_u32 v4, v4, v8, s69
	global_store_short_d16_hi v[24:25], v4, off offset:64
	v_mov_b32_e32 v4, v213
	v_add_u32_e32 v22, 1, v20
	v_ashrrev_i32_e32 v23, 31, v22
	s_nop 0
	v_lshlrev_b32_e32 v4, 16, v4
	v_mul_f32_e32 v0, v0, v4
	v_bfe_u32 v4, v0, 16, 1
	v_add3_u32 v0, v0, v4, s69
	global_store_short_d16_hi v[24:25], v0, off offset:96
	v_mad_i64_i32 v[24:25], s[6:7], v22, s68, v[18:19]
	v_lshl_add_u64 v[24:25], v[24:25], 0, v[96:97]
	v_mov_b32_e32 v4, v214
	ds_bpermute_b32 v0, v141, v26
	v_lshlrev_b64 v[22:23], 12, v[22:23]
	v_lshl_add_u64 v[22:23], v[16:17], 0, v[22:23]
	s_waitcnt lgkmcnt(0)
; __device__ __forceinline__ bf16_t f2bf(float f) { unsigned u = __float_as_uint(f); u += 0x7FFFu + ((u >> 16) & 1u); return (bf16_t)(u >> 16); }
; __device__ __forceinline__ float bf2f(bf16_t b) { return __uint_as_float(((unsigned)b) << 16); }
; __device__ void attn_phase(PP p, int layer) {
;     ...
;     for (int task = blockIdx.x * 8 + wid; task < ntask; task += gridDim.x * 8) {
;     ...
;         for (int jj = 0; jj < 4; ++jj) { const float ij = __shfl(inv, quad * 4 + jj); const int tok = tq0 + quad * 4 + jj;
; #pragma unroll
;             for (int dt = 0; dt < 4; ++dt) { const int d = dt * 16 + qi; const float z = bf2f(PROJ[(size_t)tok * NIN + 1536 + head * 64 + d]);
;                 U[(size_t)tok * DM + head * 64 + d] = f2bf(O[dt][jj] * ij * z); } }
	v_mul_f32_e32 v8, v13, v0
	v_lshl_add_u64 v[12:13], v[22:23], 0, v[96:97]
	v_mul_f32_e32 v5, v5, v0
	s_nop 0
	v_lshlrev_b32_e32 v4, 16, v4
	v_mul_f32_e32 v4, v8, v4
	v_bfe_u32 v8, v4, 16, 1
	v_add3_u32 v4, v4, v8, s69
	global_store_short_d16_hi v[12:13], v4, off
	v_mov_b32_e32 v4, v215
	v_mul_f32_e32 v8, v9, v0
	v_mul_f32_e32 v0, v1, v0
	s_nop 0
	v_lshlrev_b32_e32 v4, 16, v4
	v_mul_f32_e32 v4, v8, v4
	v_bfe_u32 v8, v4, 16, 1
	v_add3_u32 v4, v4, v8, s69
	global_store_short_d16_hi v[12:13], v4, off offset:32
	v_mov_b32_e32 v4, v216
	ds_bpermute_b32 v8, v142, v26
	s_waitcnt lgkmcnt(0)
	v_mul_f32_e32 v10, v10, v8
	v_mul_f32_e32 v6, v6, v8
	v_mul_f32_e32 v2, v2, v8
	s_nop 0
	v_lshlrev_b32_e32 v4, 16, v4
	v_mul_f32_e32 v4, v5, v4
	v_bfe_u32 v5, v4, 16, 1
	v_add3_u32 v4, v4, v5, s69
	global_store_short_d16_hi v[12:13], v4, off offset:64
	v_mov_b32_e32 v4, v217
	s_nop 0
	v_lshlrev_b32_e32 v4, 16, v4
	v_mul_f32_e32 v0, v0, v4
	v_bfe_u32 v1, v0, 16, 1
	v_add3_u32 v0, v0, v1, s69
	global_store_short_d16_hi v[12:13], v0, off offset:96
	v_add_u32_e32 v0, 2, v20
	v_mad_i64_i32 v[4:5], s[6:7], v0, s68, v[18:19]
	v_lshl_add_u64 v[4:5], v[4:5], 0, v[96:97]
	v_mov_b32_e32 v9, v218
	v_ashrrev_i32_e32 v1, 31, v0
	v_mul_f32_e32 v12, v14, v8
	v_lshlrev_b64 v[0:1], 12, v[0:1]
	v_lshl_add_u64 v[0:1], v[16:17], 0, v[0:1]
	v_lshl_add_u64 v[0:1], v[0:1], 0, v[96:97]
	s_nop 0
	v_lshlrev_b32_e32 v9, 16, v9
	v_mul_f32_e32 v9, v12, v9
	v_bfe_u32 v12, v9, 16, 1
	v_add3_u32 v9, v9, v12, s69
	global_store_short_d16_hi v[0:1], v9, off
	v_mov_b32_e32 v9, v219
	s_nop 0
	v_lshlrev_b32_e32 v9, 16, v9
	v_mul_f32_e32 v9, v10, v9
	v_bfe_u32 v10, v9, 16, 1
	v_add3_u32 v9, v9, v10, s69
	global_store_short_d16_hi v[0:1], v9, off offset:32
	v_mov_b32_e32 v9, v220
	s_nop 0
	v_lshlrev_b32_e32 v9, 16, v9
	v_mov_b32_e32 v4, v221
	v_mul_f32_e32 v6, v6, v9
	v_bfe_u32 v9, v6, 16, 1
	v_add3_u32 v6, v6, v9, s69
	global_store_short_d16_hi v[0:1], v6, off offset:64
	s_nop 0
	v_lshlrev_b32_e32 v4, 16, v4
	v_mul_f32_e32 v2, v2, v4
	v_bfe_u32 v4, v2, 16, 1
	v_add3_u32 v2, v2, v4, s69
	global_store_short_d16_hi v[0:1], v2, off offset:96
	v_add_u32_e32 v0, 3, v20
	v_mad_i64_i32 v[4:5], s[6:7], v0, s68, v[18:19]
	v_lshl_add_u64 v[4:5], v[4:5], 0, v[96:97]
	v_mov_b32_e32 v6, v222
	ds_bpermute_b32 v2, v143, v26
	v_ashrrev_i32_e32 v1, 31, v0
	v_lshlrev_b64 v[0:1], 12, v[0:1]
	v_lshl_add_u64 v[0:1], v[16:17], 0, v[0:1]
	v_lshl_add_u64 v[0:1], v[0:1], 0, v[96:97]
	s_waitcnt lgkmcnt(0)
	v_mul_f32_e32 v8, v15, v2
	v_mul_f32_e32 v7, v7, v2
	v_readlane_b32 s6, v249, 26
	s_nop 0
	v_lshlrev_b32_e32 v6, 16, v6
	v_mul_f32_e32 v6, v8, v6
	v_bfe_u32 v8, v6, 16, 1
	v_add3_u32 v6, v6, v8, s69
	global_store_short_d16_hi v[0:1], v6, off
	v_mov_b32_e32 v6, v223
	v_mul_f32_e32 v8, v11, v2
	v_mul_f32_e32 v2, v3, v2
	v_add_u32_e32 v89, s6, v89
	v_cmp_lt_u32_e32 vcc, 0x21ff, v89
	s_nop 1
	v_cndmask_b32_e32 v231, 0, v230, vcc
	v_sub_u32_e32 v89, v89, v231
	v_cmp_le_i32_e32 vcc, s4, v89
	s_or_b64 s[60:61], vcc, s[60:61]
	s_nop 0
	v_lshlrev_b32_e32 v6, 16, v6
	v_mul_f32_e32 v6, v8, v6
	v_bfe_u32 v8, v6, 16, 1
	v_add3_u32 v6, v6, v8, s69
	global_store_short_d16_hi v[0:1], v6, off offset:32
	v_mov_b32_e32 v6, v224
	s_nop 0
	v_lshlrev_b32_e32 v6, 16, v6
	v_mov_b32_e32 v4, v225
	v_mul_f32_e32 v6, v7, v6
	v_bfe_u32 v7, v6, 16, 1
	v_add3_u32 v6, v6, v7, s69
	global_store_short_d16_hi v[0:1], v6, off offset:64
	s_nop 0
	v_lshlrev_b32_e32 v4, 16, v4
	v_mul_f32_e32 v2, v2, v4
	v_bfe_u32 v3, v2, 16, 1
	v_add3_u32 v2, v2, v3, s69
	global_store_short_d16_hi v[0:1], v2, off offset:96
	s_andn2_b64 exec, exec, s[60:61]
	s_cbranch_execz .LBB0_403
